# v040priolo
# speedup vs baseline: 1.0001x; 1.0001x over previous
; DEV char* opaque_ptr(char* q) { asm volatile("" : "+s"(q)); return q; }
; __global__ void __launch_bounds__(512, 2) mega(P p) {
;   cg::grid_group grid = cg::this_grid();
;   extern __shared__ __attribute__((aligned(16))) HALF sm[];
;   char* ws = opaque_ptr(p.ws);
;   const int nb = gridDim.x;
;   const int hf = __builtin_amdgcn_readfirstlane((int)(threadIdx.x >> 8));
_Z4mega1P:
	s_load_dwordx16 s[48:63], s[0:1], 0x0
	s_load_dwordx8 s[24:31], s[0:1], 0x60
	s_load_dwordx8 s[4:11], s[0:1], 0x40
	s_add_u32 s44, s0, 0x78
	s_addc_u32 s45, s1, 0
	s_load_dword s34, s[0:1], 0x80
	s_waitcnt lgkmcnt(0)
	s_mov_b64 s[0:1], s[28:29]
	v_writelane_b32 v254, s4, 0
	s_mov_b32 s3, 0
	v_and_b32_e32 v155, 0x3ff, v0
	v_writelane_b32 v254, s5, 1
	v_writelane_b32 v254, s6, 2
	v_writelane_b32 v254, s7, 3
	v_writelane_b32 v254, s8, 4
	v_writelane_b32 v254, s9, 5
	v_writelane_b32 v254, s10, 6
	v_writelane_b32 v254, s11, 7
	v_writelane_b32 v254, s0, 8
	s_mov_b32 s38, s30
	v_readfirstlane_b32 s33, v155
	s_nop 3
	s_cmp_lt_u32 s33, 0x100
	s_cbranch_scc0 .Lprio_done
	s_setprio 1
